# NSA sel/win loops: row-max tree skipped on steady-state tiles (row-sum <= 2^16 check before accumulation, classic redo otherwise); diff redo guard
# speedup vs baseline: 1.0705x; 1.0139x over previous
.Lmy_noredo:
	v_pk_add_f32 v[178:179], v[142:143], v[178:179]
	v_cvt_pk_bf16_f32 v142, v167, v195
	v_cvt_pk_bf16_f32 v143, v169, v203
	v_cvt_pk_bf16_f32 v144, v163, v205
	v_cvt_pk_bf16_f32 v145, v165, v207
	v_cvt_pk_bf16_f32 v150, v159, v209
	v_cvt_pk_bf16_f32 v151, v161, v211
	v_cvt_pk_bf16_f32 v152, v155, v213
	v_cvt_pk_bf16_f32 v153, v157, v217
	ds_read_b128 v[154:157], v0 offset:16384
	ds_read_b128 v[158:161], v0 offset:17408
	ds_read_b128 v[162:165], v0 offset:18432
	ds_read_b128 v[166:169], v0 offset:19456
	ds_read_b128 v[202:205], v0 offset:20480
	ds_read_b128 v[206:209], v0 offset:21504
	ds_read_b128 v[210:213], v0 offset:22528
	ds_read_b128 v[216:219], v0 offset:23552
	s_waitcnt lgkmcnt(8)
	v_mfma_f32_16x16x32_bf16 v[90:93], v[134:137], v[146:149], v[90:93]
	v_mfma_f32_16x16x32_bf16 v[70:73], v[134:137], v[142:145], v[70:73]
	v_mfma_f32_16x16x32_bf16 v[102:105], v[126:129], v[146:149], v[102:105]
	v_mfma_f32_16x16x32_bf16 v[66:69], v[126:129], v[142:145], v[66:69]
	v_mfma_f32_16x16x32_bf16 v[98:101], v[118:121], v[146:149], v[98:101]
	v_mfma_f32_16x16x32_bf16 v[58:61], v[118:121], v[142:145], v[58:61]
	v_mfma_f32_16x16x32_bf16 v[94:97], v[110:113], v[146:149], v[94:97]
	v_mfma_f32_16x16x32_bf16 v[54:57], v[110:113], v[142:145], v[54:57]
	s_waitcnt lgkmcnt(7)
	v_mfma_f32_16x16x32_bf16 v[86:89], v[154:157], v[146:149], v[86:89]
	v_mfma_f32_16x16x32_bf16 v[46:49], v[154:157], v[142:145], v[46:49]
	s_waitcnt lgkmcnt(5)
	v_mfma_f32_16x16x32_bf16 v[82:85], v[162:165], v[146:149], v[82:85]
	v_mfma_f32_16x16x32_bf16 v[38:41], v[162:165], v[142:145], v[38:41]
	s_waitcnt lgkmcnt(3)
	v_mfma_f32_16x16x32_bf16 v[78:81], v[202:205], v[146:149], v[78:81]
	v_mfma_f32_16x16x32_bf16 v[34:37], v[202:205], v[142:145], v[34:37]
	s_waitcnt lgkmcnt(1)
	v_mfma_f32_16x16x32_bf16 v[74:77], v[210:213], v[146:149], v[74:77]
	v_mfma_f32_16x16x32_bf16 v[26:29], v[210:213], v[142:145], v[26:29]
	v_mfma_f32_16x16x32_bf16 v[90:93], v[130:133], v[138:141], v[90:93]
	v_mfma_f32_16x16x32_bf16 v[70:73], v[130:133], v[150:153], v[70:73]
	v_mfma_f32_16x16x32_bf16 v[102:105], v[122:125], v[138:141], v[102:105]
	v_mfma_f32_16x16x32_bf16 v[66:69], v[122:125], v[150:153], v[66:69]
	v_mfma_f32_16x16x32_bf16 v[98:101], v[114:117], v[138:141], v[98:101]
	v_mfma_f32_16x16x32_bf16 v[58:61], v[114:117], v[150:153], v[58:61]
	v_mfma_f32_16x16x32_bf16 v[94:97], v[106:109], v[138:141], v[94:97]
	v_mfma_f32_16x16x32_bf16 v[54:57], v[106:109], v[150:153], v[54:57]
	v_mfma_f32_16x16x32_bf16 v[86:89], v[158:161], v[138:141], v[86:89]
	v_mfma_f32_16x16x32_bf16 v[46:49], v[158:161], v[150:153], v[46:49]
	v_mfma_f32_16x16x32_bf16 v[82:85], v[166:169], v[138:141], v[82:85]
	v_mfma_f32_16x16x32_bf16 v[38:41], v[166:169], v[150:153], v[38:41]
	v_mfma_f32_16x16x32_bf16 v[78:81], v[206:209], v[138:141], v[78:81]
	v_mfma_f32_16x16x32_bf16 v[34:37], v[206:209], v[150:153], v[34:37]
	s_waitcnt lgkmcnt(0)
	v_mfma_f32_16x16x32_bf16 v[74:77], v[216:219], v[138:141], v[74:77]
	v_mfma_f32_16x16x32_bf16 v[26:29], v[216:219], v[150:153], v[26:29]
	s_xor_b32 s53, s53, 1
	s_add_i32 s49, s49, 64
	s_add_i32 s54, s54, 1
	s_add_u32 s98, s98, 0x4000
	s_addc_u32 s99, s99, 0
	s_add_u32 s2, s2, 0x2000
	s_addc_u32 s3, s3, 0
	s_cmp_lg_u32 s1, s54
	s_cbranch_scc0 .LBB0_42
	s_mov_b32 s101, 0
	s_branch .LBB0_46
.Lmy_redo:
	s_cmp_eq_u32 s101, 1
	s_cbranch_scc1 .Lmy_noredo
	s_mov_b32 s101, 1
	s_mul_i32 s40, s53, 0x6000
	s_branch .LBB0_48

.LBB0_394:
	v_lshlrev_b32_e32 v9, 16, v82
	v_lshlrev_b32_e32 v8, 16, v86
	v_mov_b32_e32 v24, v78
	v_mov_b32_e32 v25, v74
	v_pk_mul_f32 v[24:25], v[24:25], v[8:9]
	v_and_b32_e32 v11, 0xffff0000, v82
	v_sub_f32_e32 v0, v24, v25
	v_mov_b32_e32 v24, v74
	v_mov_b32_e32 v25, v78
	v_and_b32_e32 v10, 0xffff0000, v86
	v_pk_mul_f32 v[8:9], v[24:25], v[8:9]
	v_mov_b32_e32 v74, v79
	v_add_f32_e32 v5, v8, v9
	v_cmp_gt_u32_e32 vcc, 32, v185
	v_pk_mul_f32 v[8:9], v[74:75], v[10:11]
	v_mov_b32_e32 v78, v75
	v_cndmask_b32_e32 v0, v5, v0, vcc
	v_sub_f32_e32 v5, v8, v9
	v_pk_mul_f32 v[8:9], v[78:79], v[10:11]
	v_lshlrev_b32_e32 v13, 16, v83
	v_lshlrev_b32_e32 v12, 16, v87
	v_add_f32_e32 v7, v9, v8
	v_mov_b32_e32 v8, v80
	v_mov_b32_e32 v9, v76
	v_pk_mul_f32 v[8:9], v[8:9], v[12:13]
	v_cndmask_b32_e32 v5, v7, v5, vcc
	v_sub_f32_e32 v7, v8, v9
	v_mov_b32_e32 v8, v76
	v_mov_b32_e32 v9, v80
	v_pk_mul_f32 v[8:9], v[8:9], v[12:13]
	v_and_b32_e32 v15, 0xffff0000, v83
	v_and_b32_e32 v14, 0xffff0000, v87
	v_add_f32_e32 v8, v9, v8
	v_mov_b32_e32 v76, v81
	v_cndmask_b32_e32 v7, v8, v7, vcc
	v_pk_mul_f32 v[8:9], v[76:77], v[14:15]
	v_mov_b32_e32 v80, v77
	v_sub_f32_e32 v10, v8, v9
	v_pk_mul_f32 v[8:9], v[80:81], v[14:15]
	v_lshlrev_b32_e32 v17, 16, v84
	v_add_f32_e32 v8, v9, v8
	v_lshlrev_b32_e32 v16, 16, v88
	v_cndmask_b32_e32 v10, v8, v10, vcc
	v_mov_b32_e32 v8, v70
	v_mov_b32_e32 v9, v66
	v_pk_mul_f32 v[8:9], v[8:9], v[16:17]
	v_and_b32_e32 v19, 0xffff0000, v84
	v_sub_f32_e32 v11, v8, v9
	v_mov_b32_e32 v8, v66
	v_mov_b32_e32 v9, v70
	v_pk_mul_f32 v[8:9], v[8:9], v[16:17]
	v_and_b32_e32 v18, 0xffff0000, v88
	v_add_f32_e32 v8, v9, v8
	v_mov_b32_e32 v66, v71
	v_cndmask_b32_e32 v11, v8, v11, vcc
	v_pk_mul_f32 v[8:9], v[66:67], v[18:19]
	v_mov_b32_e32 v70, v67
	v_sub_f32_e32 v12, v8, v9
	v_pk_mul_f32 v[8:9], v[70:71], v[18:19]
	v_lshlrev_b32_e32 v21, 16, v85
	v_add_f32_e32 v8, v9, v8
	v_lshlrev_b32_e32 v20, 16, v89
	v_cndmask_b32_e32 v12, v8, v12, vcc
	v_mov_b32_e32 v8, v72
	v_mov_b32_e32 v9, v68
	v_pk_mul_f32 v[8:9], v[8:9], v[20:21]
	v_and_b32_e32 v23, 0xffff0000, v85
	v_sub_f32_e32 v13, v8, v9
	v_mov_b32_e32 v8, v68
	v_mov_b32_e32 v9, v72
	v_pk_mul_f32 v[8:9], v[8:9], v[20:21]
	v_and_b32_e32 v22, 0xffff0000, v89
	v_add_f32_e32 v8, v9, v8
	v_mov_b32_e32 v68, v73
	v_cndmask_b32_e32 v13, v8, v13, vcc
	v_pk_mul_f32 v[8:9], v[68:69], v[22:23]
	v_mov_b32_e32 v72, v69
	v_sub_f32_e32 v14, v8, v9
	v_pk_mul_f32 v[8:9], v[72:73], v[22:23]
	s_lshl_b32 s46, s75, 3
	v_add_f32_e32 v8, v9, v8
	s_add_i32 s46, s46, s74
	v_cndmask_b32_e32 v8, v8, v14, vcc
	v_mov_b32_e32 v81, 0
	v_cvt_pk_bf16_f32 v142, v0, v5
	v_cvt_pk_bf16_f32 v143, v7, v10
	v_cvt_pk_bf16_f32 v144, v11, v12
	v_cvt_pk_bf16_f32 v145, v13, v8
	s_cmp_gt_u32 s94, s80
	v_mov_b32_e32 v80, v81
	v_mov_b32_e32 v79, v81
	v_mov_b32_e32 v78, v81
	v_mov_b32_e32 v77, v81
	v_mov_b32_e32 v76, v81
	v_mov_b32_e32 v75, v81
	v_mov_b32_e32 v74, v81
	v_mov_b32_e32 v73, v81
	v_mov_b32_e32 v72, v81
	v_mov_b32_e32 v71, v81
	v_mov_b32_e32 v70, v81
	v_mov_b32_e32 v69, v81
	v_mov_b32_e32 v68, v81
	v_mov_b32_e32 v67, v81
	v_mov_b32_e32 v66, v81
	s_waitcnt vmcnt(6)
	v_mov_b32_e32 v97, v81
	v_mov_b32_e32 v96, v81
	v_mov_b32_e32 v95, v81
	v_mov_b32_e32 v94, v81
	v_mov_b32_e32 v93, v81
	v_mov_b32_e32 v92, v81
	v_mov_b32_e32 v91, v81
	v_mov_b32_e32 v90, v81
	v_mov_b32_e32 v89, v81
	v_mov_b32_e32 v88, v81
	v_mov_b32_e32 v87, v81
	v_mov_b32_e32 v86, v81
	v_mov_b32_e32 v85, v81
	v_mov_b32_e32 v84, v81
	v_mov_b32_e32 v83, v81
	v_mov_b32_e32 v82, v81
	v_mov_b32_e32 v201, v81
	s_cbranch_scc1 .LBB0_410
	v_lshrrev_b32_e32 v5, 3, v6
	v_lshlrev_b32_e32 v166, 4, v6
	v_and_b32_e32 v168, 4, v5
	v_ashrrev_i32_e32 v5, 31, v4
	v_mov_b32_e32 v201, 0
	v_lshlrev_b32_e32 v0, 4, v184
	v_and_b32_e32 v167, 0x3f0, v166
	s_mov_b32 s49, 0
	v_mov_b32_e32 v170, 0xf149f2ca
	v_lshlrev_b64 v[162:163], 1, v[2:3]
	v_lshlrev_b64 v[164:165], 1, v[4:5]
	v_mov_b32_e32 v82, 0
	v_mov_b32_e32 v83, v201
	v_mov_b32_e32 v84, v201
	v_mov_b32_e32 v85, v201
	v_mov_b32_e32 v86, v201
	v_mov_b32_e32 v87, v201
	v_mov_b32_e32 v88, v201
	v_mov_b32_e32 v89, v201
	v_mov_b32_e32 v90, v201
	v_mov_b32_e32 v91, v201
	v_mov_b32_e32 v92, v201
	v_mov_b32_e32 v93, v201
	v_mov_b32_e32 v94, v201
	v_mov_b32_e32 v95, v201
	v_mov_b32_e32 v96, v201
	v_mov_b32_e32 v97, v201
	v_mov_b32_e32 v66, v201
	v_mov_b32_e32 v67, v201
	v_mov_b32_e32 v68, v201
	v_mov_b32_e32 v69, v201
	v_mov_b32_e32 v70, v201
	v_mov_b32_e32 v71, v201
	v_mov_b32_e32 v72, v201
	v_mov_b32_e32 v73, v201
	v_mov_b32_e32 v74, v201
	v_mov_b32_e32 v75, v201
	v_mov_b32_e32 v76, v201
	v_mov_b32_e32 v77, v201
	v_mov_b32_e32 v78, v201
	v_mov_b32_e32 v79, v201
	v_mov_b32_e32 v80, v201
	v_mov_b32_e32 v81, v201
	s_waitcnt vmcnt(0)
	ds_write_b128 v166, v[98:101]
	ds_write_b128 v166, v[102:105] offset:4096
	ds_write_b128 v166, v[106:109] offset:8192
	ds_write_b128 v166, v[110:113] offset:12288
	s_mov_b32 s101, 1

.Lmy_qk_s:
	v_add_u32_e32 v169, s52, v167
	ds_read_b128 v[2:5], v169
	ds_read_b128 v[114:117], v169 offset:1024
	ds_read_b128 v[118:121], v169 offset:2048
	ds_read_b128 v[122:125], v169 offset:3072
	ds_read_b128 v[6:9], v169 offset:4096
	ds_read_b128 v[126:129], v169 offset:5120
	ds_read_b128 v[146:149], v169 offset:6144
	ds_read_b128 v[172:175], v169 offset:7168
	s_waitcnt lgkmcnt(7)
	v_mfma_f32_32x32x16_bf16 v[18:33], v[2:5], v[142:145], 0
	s_waitcnt lgkmcnt(3)
	v_mfma_f32_32x32x16_bf16 v[2:17], v[6:9], v[142:145], 0
	v_mfma_f32_32x32x16_bf16 v[18:33], v[114:117], v[130:133], v[18:33]
	s_waitcnt lgkmcnt(2)
	v_mfma_f32_32x32x16_bf16 v[2:17], v[126:129], v[130:133], v[2:17]
	v_mfma_f32_32x32x16_bf16 v[18:33], v[118:121], v[134:137], v[18:33]
	s_waitcnt lgkmcnt(1)
	v_mfma_f32_32x32x16_bf16 v[2:17], v[146:149], v[134:137], v[2:17]
	v_mfma_f32_32x32x16_bf16 v[18:33], v[122:125], v[138:141], v[18:33]
	ds_read_b128 v[158:161], v169 offset:8192
	ds_read_b128 v[154:157], v169 offset:9216
	ds_read_b128 v[150:153], v169 offset:10240
	ds_read_b128 v[146:149], v169 offset:11264
	ds_read_b128 v[126:129], v169 offset:12288
	ds_read_b128 v[122:125], v169 offset:13312
	ds_read_b128 v[118:121], v169 offset:14336
	ds_read_b128 v[114:117], v169 offset:15360
	s_waitcnt lgkmcnt(8)
	v_mfma_f32_32x32x16_bf16 v[2:17], v[172:175], v[138:141], v[2:17]
	s_lshl_b32 s0, s94, 6
	s_or_b32 s12, s0, 63
	s_cmp_le_i32 s12, s46
	s_cbranch_scc1 .LBB0_405
	v_or_b32_e32 v169, s0, v168
	v_or_b32_e32 v171, 32, v169
	v_cmp_le_i32_e32 vcc, v169, v200
	v_or_b32_e32 v172, 34, v169
	s_nop 0
	v_cndmask_b32_e32 v18, v222, v18, vcc
	v_cmp_le_i32_e32 vcc, v171, v200
	v_or_b32_e32 v171, 33, v169
	s_nop 0
	v_cndmask_b32_e32 v2, v222, v2, vcc
	v_cmp_lt_i32_e32 vcc, v169, v200
	s_nop 1
	v_cndmask_b32_e32 v19, v222, v19, vcc
	v_cmp_le_i32_e32 vcc, v171, v200
	v_or_b32_e32 v171, 2, v169
	s_nop 0
	v_cndmask_b32_e32 v3, v222, v3, vcc
	v_cmp_le_i32_e32 vcc, v171, v200
	v_or_b32_e32 v171, 3, v169
	s_nop 0
	v_cndmask_b32_e32 v20, v222, v20, vcc
	v_cmp_le_i32_e32 vcc, v172, v200
	v_or_b32_e32 v172, 35, v169
	s_nop 0
	v_cndmask_b32_e32 v4, v222, v4, vcc
	v_cmp_le_i32_e32 vcc, v171, v200
	v_or_b32_e32 v171, 8, v169
	s_nop 0
	v_cndmask_b32_e32 v21, v222, v21, vcc
	v_cmp_le_i32_e32 vcc, v172, v200
	v_or_b32_e32 v172, 40, v169
	s_nop 0
	v_cndmask_b32_e32 v5, v222, v5, vcc
	v_cmp_le_i32_e32 vcc, v171, v200
	v_or_b32_e32 v171, 9, v169
	s_nop 0
	v_cndmask_b32_e32 v22, v222, v22, vcc
	v_cmp_le_i32_e32 vcc, v172, v200
	v_or_b32_e32 v172, 41, v169
	s_nop 0
	v_cndmask_b32_e32 v6, v222, v6, vcc
	v_cmp_le_i32_e32 vcc, v171, v200
	v_or_b32_e32 v171, 10, v169
	s_nop 0
	v_cndmask_b32_e32 v23, v222, v23, vcc
	v_cmp_le_i32_e32 vcc, v172, v200
	v_or_b32_e32 v172, 42, v169
	s_nop 0
	v_cndmask_b32_e32 v7, v222, v7, vcc
	v_cmp_le_i32_e32 vcc, v171, v200
	v_or_b32_e32 v171, 11, v169
	s_nop 0
	v_cndmask_b32_e32 v24, v222, v24, vcc
	v_cmp_le_i32_e32 vcc, v172, v200
	v_or_b32_e32 v172, 43, v169
	s_nop 0
	v_cndmask_b32_e32 v8, v222, v8, vcc
	v_cmp_le_i32_e32 vcc, v171, v200
	v_or_b32_e32 v171, 16, v169
	s_nop 0
	v_cndmask_b32_e32 v25, v222, v25, vcc
	v_cmp_le_i32_e32 vcc, v172, v200
	v_or_b32_e32 v172, 48, v169
	s_nop 0
	v_cndmask_b32_e32 v9, v222, v9, vcc
	v_cmp_le_i32_e32 vcc, v171, v200
	v_or_b32_e32 v171, 17, v169
	s_nop 0
	v_cndmask_b32_e32 v26, v222, v26, vcc
	v_cmp_le_i32_e32 vcc, v172, v200
	v_or_b32_e32 v172, 49, v169
	s_nop 0
	v_cndmask_b32_e32 v10, v222, v10, vcc
	v_cmp_le_i32_e32 vcc, v171, v200
	v_or_b32_e32 v171, 18, v169
	s_nop 0
	v_cndmask_b32_e32 v27, v222, v27, vcc
	v_cmp_le_i32_e32 vcc, v172, v200
	v_or_b32_e32 v172, 50, v169
	s_nop 0
	v_cndmask_b32_e32 v11, v222, v11, vcc
	v_cmp_le_i32_e32 vcc, v171, v200
	v_or_b32_e32 v171, 19, v169
	s_nop 0
	v_cndmask_b32_e32 v28, v222, v28, vcc
	v_cmp_le_i32_e32 vcc, v172, v200
	v_or_b32_e32 v172, 51, v169
	s_nop 0
	v_cndmask_b32_e32 v12, v222, v12, vcc
	v_cmp_le_i32_e32 vcc, v171, v200
	v_or_b32_e32 v171, 24, v169
	s_nop 0
	v_cndmask_b32_e32 v29, v222, v29, vcc
	v_cmp_le_i32_e32 vcc, v172, v200
	v_or_b32_e32 v172, 56, v169
	s_nop 0
	v_cndmask_b32_e32 v13, v222, v13, vcc
	v_cmp_le_i32_e32 vcc, v171, v200
	v_or_b32_e32 v171, 25, v169
	s_nop 0
	v_cndmask_b32_e32 v30, v222, v30, vcc
	v_cmp_le_i32_e32 vcc, v172, v200
	v_or_b32_e32 v172, 57, v169
	s_nop 0
	v_cndmask_b32_e32 v14, v222, v14, vcc
	v_cmp_le_i32_e32 vcc, v171, v200
	v_or_b32_e32 v171, 26, v169
	s_nop 0
	v_cndmask_b32_e32 v31, v222, v31, vcc
	v_cmp_le_i32_e32 vcc, v172, v200
	v_or_b32_e32 v172, 58, v169
	s_nop 0
	v_cndmask_b32_e32 v15, v222, v15, vcc
	v_cmp_le_i32_e32 vcc, v171, v200
	v_or_b32_e32 v171, 27, v169
	v_or_b32_e32 v169, 59, v169
	v_cndmask_b32_e32 v32, v222, v32, vcc
	v_cmp_le_i32_e32 vcc, v172, v200
	s_nop 1
	v_cndmask_b32_e32 v16, v222, v16, vcc
	v_cmp_le_i32_e32 vcc, v171, v200
	s_nop 1
	v_cndmask_b32_e32 v33, v222, v33, vcc
	v_cmp_le_i32_e32 vcc, v169, v200
	s_nop 1
	v_cndmask_b32_e32 v17, v222, v17, vcc
.LBB0_405:
	s_cmp_eq_u32 s101, 0
	s_cbranch_scc1 .Lmy_lazy_0
	v_max3_f32 v169, v18, v19, v20
	v_max3_f32 v171, v21, v22, v23
	v_max3_f32 v172, v24, v25, v26
	v_max3_f32 v169, v169, v27, v28
	v_max3_f32 v171, v171, v29, v30
	v_max3_f32 v172, v172, v31, v32
	v_max3_f32 v169, v169, v171, v33
	v_max_f32_e32 v169, v169, v172
	v_max3_f32 v171, v2, v3, v4
	v_max3_f32 v172, v5, v6, v7
	v_max3_f32 v173, v8, v9, v10
	v_max3_f32 v171, v171, v11, v12
	v_max3_f32 v172, v172, v13, v14
	v_max3_f32 v173, v173, v15, v16
	v_max3_f32 v171, v171, v172, v17
	v_max3_f32 v169, v169, v171, v173
	v_cndmask_b32_e64 v169, v222, v169, s[40:41]
	v_mov_b32_e32 v171, v169
	s_nop 1
	v_permlane32_swap_b32_e32 v169, v171
	v_max3_f32 v169, v170, v169, v171
	v_add_f32_e32 v171, 0x42300000, v170
	v_cmp_gt_f32_e32 vcc, v169, v171
	s_cbranch_vccz .Lmy_lazy_0
	v_sub_f32_e32 v170, v170, v169
	v_mul_f32_e32 v170, 0x3e38aa3b, v170
	v_exp_f32_e32 v170, v170
	s_nop 0
	v_mul_f32_e32 v201, v201, v170
	v_pk_mul_f32 v[80:81], v[80:81], v[170:171] op_sel_hi:[1,0]
	v_pk_mul_f32 v[78:79], v[78:79], v[170:171] op_sel_hi:[1,0]
	v_pk_mul_f32 v[76:77], v[76:77], v[170:171] op_sel_hi:[1,0]
	v_pk_mul_f32 v[74:75], v[74:75], v[170:171] op_sel_hi:[1,0]
	v_pk_mul_f32 v[72:73], v[72:73], v[170:171] op_sel_hi:[1,0]
	v_pk_mul_f32 v[70:71], v[70:71], v[170:171] op_sel_hi:[1,0]
	v_pk_mul_f32 v[68:69], v[68:69], v[170:171] op_sel_hi:[1,0]
	v_pk_mul_f32 v[66:67], v[66:67], v[170:171] op_sel_hi:[1,0]
	v_pk_mul_f32 v[96:97], v[96:97], v[170:171] op_sel_hi:[1,0]
	v_pk_mul_f32 v[94:95], v[94:95], v[170:171] op_sel_hi:[1,0]
	v_pk_mul_f32 v[92:93], v[92:93], v[170:171] op_sel_hi:[1,0]
	v_pk_mul_f32 v[90:91], v[90:91], v[170:171] op_sel_hi:[1,0]
	v_pk_mul_f32 v[88:89], v[88:89], v[170:171] op_sel_hi:[1,0]
	v_pk_mul_f32 v[86:87], v[86:87], v[170:171] op_sel_hi:[1,0]
	v_pk_mul_f32 v[84:85], v[84:85], v[170:171] op_sel_hi:[1,0]
	v_pk_mul_f32 v[82:83], v[82:83], v[170:171] op_sel_hi:[1,0]
	s_branch .LBB0_407

.LBB0_407:
	v_mul_f32_e32 v170, 0xbe38aa3b, v169
	v_cndmask_b32_e64 v170, v222, v170, s[40:41]
	v_fmamk_f32 v18, v18, 0x3e38aa3b, v170
	v_fmamk_f32 v2, v2, 0x3e38aa3b, v170
	v_exp_f32_e32 v18, v18
	v_exp_f32_e32 v2, v2
	v_fmamk_f32 v19, v19, 0x3e38aa3b, v170
	v_fmamk_f32 v3, v3, 0x3e38aa3b, v170
	v_exp_f32_e32 v19, v19
	v_exp_f32_e32 v3, v3
	v_add_f32_e32 v177, v18, v2
	v_fmamk_f32 v20, v20, 0x3e38aa3b, v170
	v_fmamk_f32 v4, v4, 0x3e38aa3b, v170
	v_exp_f32_e32 v20, v20
	v_exp_f32_e32 v4, v4
	v_add_f32_e32 v176, v19, v3
	v_add_f32_e32 v177, v176, v177
	v_fmamk_f32 v21, v21, 0x3e38aa3b, v170
	v_fmamk_f32 v5, v5, 0x3e38aa3b, v170
	v_exp_f32_e32 v21, v21
	v_exp_f32_e32 v5, v5
	v_add_f32_e32 v176, v20, v4
	v_add_f32_e32 v177, v176, v177
	v_fmamk_f32 v22, v22, 0x3e38aa3b, v170
	v_fmamk_f32 v6, v6, 0x3e38aa3b, v170
	v_exp_f32_e32 v22, v22
	v_exp_f32_e32 v6, v6
	v_add_f32_e32 v176, v21, v5
	v_add_f32_e32 v177, v176, v177
	v_fmamk_f32 v23, v23, 0x3e38aa3b, v170
	v_fmamk_f32 v7, v7, 0x3e38aa3b, v170
	v_exp_f32_e32 v23, v23
	v_exp_f32_e32 v7, v7
	v_add_f32_e32 v176, v22, v6
	v_add_f32_e32 v177, v176, v177
	v_fmamk_f32 v24, v24, 0x3e38aa3b, v170
	v_fmamk_f32 v8, v8, 0x3e38aa3b, v170
	v_exp_f32_e32 v24, v24
	v_exp_f32_e32 v8, v8
	v_add_f32_e32 v176, v23, v7
	v_add_f32_e32 v177, v176, v177
	v_fmamk_f32 v25, v25, 0x3e38aa3b, v170
	v_fmamk_f32 v9, v9, 0x3e38aa3b, v170
	v_exp_f32_e32 v25, v25
	v_exp_f32_e32 v9, v9
	v_add_f32_e32 v176, v24, v8
	v_add_f32_e32 v177, v176, v177
	v_fmamk_f32 v26, v26, 0x3e38aa3b, v170
	v_fmamk_f32 v10, v10, 0x3e38aa3b, v170
	v_exp_f32_e32 v26, v26
	v_exp_f32_e32 v10, v10
	v_add_f32_e32 v176, v25, v9
	v_add_f32_e32 v177, v176, v177
	v_fmamk_f32 v27, v27, 0x3e38aa3b, v170
	v_fmamk_f32 v11, v11, 0x3e38aa3b, v170
	v_exp_f32_e32 v27, v27
	v_exp_f32_e32 v11, v11
	v_add_f32_e32 v176, v26, v10
	v_add_f32_e32 v177, v176, v177
	v_fmamk_f32 v28, v28, 0x3e38aa3b, v170
	v_fmamk_f32 v12, v12, 0x3e38aa3b, v170
	v_exp_f32_e32 v28, v28
	v_exp_f32_e32 v12, v12
	v_add_f32_e32 v176, v27, v11
	v_add_f32_e32 v177, v176, v177
	v_fmamk_f32 v29, v29, 0x3e38aa3b, v170
	v_fmamk_f32 v13, v13, 0x3e38aa3b, v170
	v_exp_f32_e32 v29, v29
	v_exp_f32_e32 v13, v13
	v_add_f32_e32 v176, v28, v12
	v_add_f32_e32 v177, v176, v177
	v_fmamk_f32 v30, v30, 0x3e38aa3b, v170
	v_fmamk_f32 v14, v14, 0x3e38aa3b, v170
	v_exp_f32_e32 v30, v30
	v_exp_f32_e32 v14, v14
	v_add_f32_e32 v176, v29, v13
	v_add_f32_e32 v177, v176, v177
	v_fmamk_f32 v31, v31, 0x3e38aa3b, v170
	v_fmamk_f32 v15, v15, 0x3e38aa3b, v170
	v_exp_f32_e32 v31, v31
	v_exp_f32_e32 v15, v15
	v_add_f32_e32 v176, v30, v14
	v_add_f32_e32 v177, v176, v177
	v_fmamk_f32 v32, v32, 0x3e38aa3b, v170
	v_fmamk_f32 v16, v16, 0x3e38aa3b, v170
	v_exp_f32_e32 v32, v32
	v_exp_f32_e32 v16, v16
	v_add_f32_e32 v176, v31, v15
	v_add_f32_e32 v177, v176, v177
	v_fmamk_f32 v33, v33, 0x3e38aa3b, v170
	v_fmamk_f32 v17, v17, 0x3e38aa3b, v170
	v_exp_f32_e32 v33, v33
	v_exp_f32_e32 v17, v17
	v_add_f32_e32 v176, v32, v16
	v_add_f32_e32 v177, v176, v177
	v_add_f32_e32 v176, v33, v17
	v_add_f32_e32 v177, v176, v177
	v_cmp_lt_f32_e32 vcc, 0x47800000, v177
	s_cbranch_vccnz .Lmy_rd_s
.Lmy_nrd_s:
	v_cvt_pk_bf16_f32 v172, v18, v19
	v_cvt_pk_bf16_f32 v173, v20, v21
	v_cvt_pk_bf16_f32 v174, v22, v23
	v_cvt_pk_bf16_f32 v175, v24, v25
	v_cvt_pk_bf16_f32 v9, v8, v9
	v_cvt_pk_bf16_f32 v8, v6, v7
	s_waitcnt lgkmcnt(0)
	v_mfma_f32_32x32x16_bf16 v[82:97], v[158:161], v[172:175], v[82:97]
	v_cvt_pk_bf16_f32 v7, v4, v5
	v_cvt_pk_bf16_f32 v6, v2, v3
	v_mfma_f32_32x32x16_bf16 v[66:81], v[126:129], v[172:175], v[66:81]
	v_cvt_pk_bf16_f32 v2, v10, v11
	v_cvt_pk_bf16_f32 v3, v12, v13
	v_cvt_pk_bf16_f32 v4, v14, v15
	v_cvt_pk_bf16_f32 v5, v16, v17
	v_cvt_pk_bf16_f32 v10, v26, v27
	v_cvt_pk_bf16_f32 v11, v28, v29
	v_cvt_pk_bf16_f32 v12, v30, v31
	v_cvt_pk_bf16_f32 v13, v32, v33
	v_add_f32_e32 v201, v177, v201
	s_nop 0
	v_mfma_f32_32x32x16_bf16 v[82:97], v[154:157], v[10:13], v[82:97]
	v_mfma_f32_32x32x16_bf16 v[66:81], v[122:125], v[10:13], v[66:81]
	v_mfma_f32_32x32x16_bf16 v[82:97], v[150:153], v[6:9], v[82:97]
	v_mfma_f32_32x32x16_bf16 v[66:81], v[118:121], v[6:9], v[66:81]
	v_mfma_f32_32x32x16_bf16 v[82:97], v[146:149], v[2:5], v[82:97]
	v_mfma_f32_32x32x16_bf16 v[66:81], v[114:117], v[2:5], v[66:81]
	s_mov_b32 s101, 0
	s_xor_b32 s49, s49, 1
	s_cmp_le_i32 s1, s80
	s_cbranch_scc1 .LBB0_409
	s_branch .LBB0_410

.Lmy_rd_s:
	s_cmp_eq_u32 s101, 1
	s_cbranch_scc1 .Lmy_nrd_s
	s_mov_b32 s101, 1
	v_mov_b32_e32 v170, v169
	s_branch .Lmy_qk_s
.LBB0_410:
	ds_bpermute_b32 v221, v235, v201
	s_sub_i32 s1, 0x1de1, s77
	s_max_i32 s1, s1, 0
	s_lshl_b32 s0, s86, 19
	s_lshr_b32 s94, s1, 6
	v_mov_b32_e32 v0, v224
	v_mov_b32_e32 v33, 0
	s_cmp_gt_u32 s94, s80
	v_mov_b32_e32 v32, 0
	v_mov_b32_e32 v31, 0
	v_mov_b32_e32 v30, 0
	v_mov_b32_e32 v29, 0
	v_mov_b32_e32 v28, 0
	v_mov_b32_e32 v27, 0
	v_mov_b32_e32 v26, 0
	v_mov_b32_e32 v25, 0
	v_mov_b32_e32 v24, 0
	v_mov_b32_e32 v23, 0
	v_mov_b32_e32 v22, 0
	v_mov_b32_e32 v21, 0
	v_mov_b32_e32 v20, 0
	v_mov_b32_e32 v19, 0
	v_mov_b32_e32 v18, 0
	v_mov_b32_e32 v17, 0
	v_mov_b32_e32 v16, 0
	v_mov_b32_e32 v15, 0
	v_mov_b32_e32 v14, 0
	v_mov_b32_e32 v13, 0
	v_mov_b32_e32 v12, 0
	v_mov_b32_e32 v11, 0
	v_mov_b32_e32 v10, 0
	v_mov_b32_e32 v9, 0
	v_mov_b32_e32 v8, 0
	v_mov_b32_e32 v7, 0
	v_mov_b32_e32 v6, 0
	v_mov_b32_e32 v5, 0
	v_mov_b32_e32 v4, 0
	v_mov_b32_e32 v3, 0
	v_mov_b32_e32 v2, 0
	v_mov_b32_e32 v203, 0
	s_waitcnt lgkmcnt(0)
	s_barrier
	s_cbranch_scc1 .LBB0_235
	s_lshl_b32 s0, s0, 1
	v_readlane_b32 s1, v254, 58
	s_add_u32 s12, s1, s0
	v_readlane_b32 s1, v254, 59
	s_addc_u32 s13, s1, 0
	v_readlane_b32 s1, v254, 60
	v_lshlrev_b32_e32 v2, 3, v0
	s_add_u32 s14, s1, s0
	v_readlane_b32 s0, v254, 61
	v_ashrrev_i32_e32 v3, 31, v2
	s_addc_u32 s15, s0, 0
	s_lshl_b64 s[0:1], s[94:95], 13
	v_lshlrev_b64 v[204:205], 1, v[2:3]
	v_add_u32_e32 v2, 0x800, v2
	s_add_u32 s12, s12, s0
	v_ashrrev_i32_e32 v3, 31, v2
	s_addc_u32 s13, s13, s1
	v_lshlrev_b64 v[206:207], 1, v[2:3]
	v_lshl_add_u64 v[4:5], s[12:13], 0, v[204:205]
	v_lshl_add_u64 v[2:3], s[12:13], 0, v[206:207]
	s_add_u32 s12, s14, s0
	s_addc_u32 s13, s15, s1
	global_load_dwordx4 v[146:149], v[4:5], off
	global_load_dwordx4 v[150:153], v[2:3], off
	v_lshl_add_u64 v[2:3], s[12:13], 0, v[204:205]
	v_lshl_add_u64 v[4:5], s[12:13], 0, v[206:207]
	global_load_dwordx4 v[154:157], v[2:3], off
	global_load_dwordx4 v[158:161], v[4:5], off
	s_add_i32 s12, s46, 0xfffffe07
	s_lshl_b32 s13, s94, 6
	s_add_u32 s0, s42, s0
	v_lshlrev_b32_e32 v238, 4, v0
	v_lshrrev_b32_e32 v0, 3, v0
	s_addc_u32 s1, 0, s1
	v_readlane_b32 s14, v254, 62
	v_mov_b32_e32 v2, v1
	v_mov_b32_e32 v3, v1
	v_mov_b32_e32 v4, v1
	v_mov_b32_e32 v5, v1
	v_mov_b32_e32 v6, v1
	v_mov_b32_e32 v7, v1
	v_mov_b32_e32 v8, v1
	v_mov_b32_e32 v9, v1
	v_mov_b32_e32 v10, v1
	v_mov_b32_e32 v11, v1
	v_mov_b32_e32 v12, v1
	v_mov_b32_e32 v13, v1
	v_mov_b32_e32 v14, v1
	v_mov_b32_e32 v15, v1
	v_mov_b32_e32 v16, v1
	v_mov_b32_e32 v17, v1
	v_mov_b32_e32 v18, v1
	v_mov_b32_e32 v19, v1
	v_mov_b32_e32 v20, v1
	v_mov_b32_e32 v21, v1
	v_mov_b32_e32 v22, v1
	v_mov_b32_e32 v23, v1
	v_mov_b32_e32 v24, v1
	v_mov_b32_e32 v25, v1
	v_mov_b32_e32 v26, v1
	v_mov_b32_e32 v27, v1
	v_mov_b32_e32 v28, v1
	v_mov_b32_e32 v29, v1
	v_mov_b32_e32 v30, v1
	v_mov_b32_e32 v31, v1
	v_and_b32_e32 v240, 4, v0
	v_readlane_b32 s15, v254, 63
	s_add_u32 s0, s14, s0
	v_mov_b32_e32 v0, v1
	v_mov_b64_e32 v[32:33], v[30:31]
	v_and_b32_e32 v239, 0x3f0, v238
	v_add_u32_e32 v241, 0xfffffe00, v200
	s_addc_u32 s1, s15, s1
	s_mov_b32 s14, 0
	v_mov_b32_e32 v203, 0
	v_mov_b32_e32 v242, 0xf149f2ca
	v_mov_b64_e32 v[30:31], v[28:29]
	v_mov_b64_e32 v[28:29], v[26:27]
	v_mov_b64_e32 v[26:27], v[24:25]
	v_mov_b64_e32 v[24:25], v[22:23]
	v_mov_b64_e32 v[22:23], v[20:21]
	v_mov_b64_e32 v[20:21], v[18:19]
	v_mov_b64_e32 v[18:19], v[16:17]
	v_mov_b64_e32 v[16:17], v[14:15]
	v_mov_b64_e32 v[14:15], v[12:13]
	v_mov_b64_e32 v[12:13], v[10:11]
	v_mov_b64_e32 v[10:11], v[8:9]
	v_mov_b64_e32 v[8:9], v[6:7]
	v_mov_b64_e32 v[6:7], v[4:5]
	v_mov_b64_e32 v[4:5], v[2:3]
	v_mov_b64_e32 v[2:3], v[0:1]
	s_waitcnt vmcnt(0)
	ds_write_b128 v238, v[146:149]
	ds_write_b128 v238, v[150:153] offset:4096
	ds_write_b128 v238, v[154:157] offset:8192
	ds_write_b128 v238, v[158:161] offset:12288
	s_mov_b32 s101, 1

.LBB0_416:
	s_cmp_eq_u32 s101, 0
	s_cbranch_scc1 .Lmy_lazy_1
	v_max3_f32 v0, v114, v115, v116
	v_max3_f32 v194, v117, v118, v119
	v_max3_f32 v195, v120, v121, v122
	v_max3_f32 v0, v0, v123, v124
	v_max3_f32 v194, v194, v125, v126
	v_max3_f32 v195, v195, v127, v128
	v_max3_f32 v0, v0, v194, v129
	v_max_f32_e32 v0, v0, v195
	v_max3_f32 v194, v98, v99, v100
	v_max3_f32 v195, v101, v102, v103
	v_max3_f32 v196, v104, v105, v106
	v_max3_f32 v194, v194, v107, v108
	v_max3_f32 v195, v195, v109, v110
	v_max3_f32 v196, v196, v111, v112
	v_max3_f32 v194, v194, v195, v113
	v_max3_f32 v0, v0, v194, v196
	v_mov_b32_e32 v194, v0
	s_nop 1
	v_permlane32_swap_b32_e32 v0, v194
	v_max3_f32 v0, v242, v0, v194
	v_add_f32_e32 v194, 0x42300000, v242
	v_cmp_gt_f32_e32 vcc, v0, v194
	s_cbranch_vccz .Lmy_lazy_1
	v_sub_f32_e32 v194, v242, v0
	v_mul_f32_e32 v194, 0x3e38aa3b, v194
	v_exp_f32_e32 v194, v194
	s_nop 0
	v_mul_f32_e32 v203, v203, v194
	v_pk_mul_f32 v[32:33], v[32:33], v[194:195] op_sel_hi:[1,0]
	v_pk_mul_f32 v[30:31], v[30:31], v[194:195] op_sel_hi:[1,0]
	v_pk_mul_f32 v[28:29], v[28:29], v[194:195] op_sel_hi:[1,0]
	v_pk_mul_f32 v[26:27], v[26:27], v[194:195] op_sel_hi:[1,0]
	v_pk_mul_f32 v[24:25], v[24:25], v[194:195] op_sel_hi:[1,0]
	v_pk_mul_f32 v[22:23], v[22:23], v[194:195] op_sel_hi:[1,0]
	v_pk_mul_f32 v[20:21], v[20:21], v[194:195] op_sel_hi:[1,0]
	v_pk_mul_f32 v[18:19], v[18:19], v[194:195] op_sel_hi:[1,0]
	v_pk_mul_f32 v[16:17], v[16:17], v[194:195] op_sel_hi:[1,0]
	v_pk_mul_f32 v[14:15], v[14:15], v[194:195] op_sel_hi:[1,0]
	v_pk_mul_f32 v[12:13], v[12:13], v[194:195] op_sel_hi:[1,0]
	v_pk_mul_f32 v[10:11], v[10:11], v[194:195] op_sel_hi:[1,0]
	v_pk_mul_f32 v[8:9], v[8:9], v[194:195] op_sel_hi:[1,0]
	v_pk_mul_f32 v[6:7], v[6:7], v[194:195] op_sel_hi:[1,0]
	v_pk_mul_f32 v[4:5], v[4:5], v[194:195] op_sel_hi:[1,0]
	v_pk_mul_f32 v[2:3], v[2:3], v[194:195] op_sel_hi:[1,0]
	s_branch .LBB0_418

.LBB0_418:
	v_mul_f32_e32 v194, 0xbe38aa3b, v0
	v_fmamk_f32 v114, v114, 0x3e38aa3b, v194
	v_fmamk_f32 v98, v98, 0x3e38aa3b, v194
	v_exp_f32_e32 v114, v114
	v_exp_f32_e32 v98, v98
	v_fmamk_f32 v115, v115, 0x3e38aa3b, v194
	v_fmamk_f32 v99, v99, 0x3e38aa3b, v194
	v_exp_f32_e32 v115, v115
	v_exp_f32_e32 v99, v99
	v_add_f32_e32 v196, v114, v98
	v_fmamk_f32 v116, v116, 0x3e38aa3b, v194
	v_fmamk_f32 v100, v100, 0x3e38aa3b, v194
	v_exp_f32_e32 v116, v116
	v_exp_f32_e32 v100, v100
	v_add_f32_e32 v195, v115, v99
	v_add_f32_e32 v196, v195, v196
	v_fmamk_f32 v117, v117, 0x3e38aa3b, v194
	v_fmamk_f32 v101, v101, 0x3e38aa3b, v194
	v_exp_f32_e32 v117, v117
	v_exp_f32_e32 v101, v101
	v_add_f32_e32 v195, v116, v100
	v_add_f32_e32 v196, v195, v196
	v_fmamk_f32 v118, v118, 0x3e38aa3b, v194
	v_fmamk_f32 v102, v102, 0x3e38aa3b, v194
	v_exp_f32_e32 v118, v118
	v_exp_f32_e32 v102, v102
	v_add_f32_e32 v195, v117, v101
	v_add_f32_e32 v196, v195, v196
	v_fmamk_f32 v119, v119, 0x3e38aa3b, v194
	v_fmamk_f32 v103, v103, 0x3e38aa3b, v194
	v_exp_f32_e32 v119, v119
	v_exp_f32_e32 v103, v103
	v_add_f32_e32 v195, v118, v102
	v_add_f32_e32 v196, v195, v196
	v_fmamk_f32 v120, v120, 0x3e38aa3b, v194
	v_fmamk_f32 v104, v104, 0x3e38aa3b, v194
	v_exp_f32_e32 v120, v120
	v_exp_f32_e32 v104, v104
	v_add_f32_e32 v195, v119, v103
	v_add_f32_e32 v196, v195, v196
	v_fmamk_f32 v121, v121, 0x3e38aa3b, v194
	v_fmamk_f32 v105, v105, 0x3e38aa3b, v194
	v_exp_f32_e32 v121, v121
	v_exp_f32_e32 v105, v105
	v_add_f32_e32 v195, v120, v104
	v_add_f32_e32 v196, v195, v196
	v_fmamk_f32 v122, v122, 0x3e38aa3b, v194
	v_fmamk_f32 v106, v106, 0x3e38aa3b, v194
	v_exp_f32_e32 v122, v122
	v_exp_f32_e32 v106, v106
	v_add_f32_e32 v195, v121, v105
	v_add_f32_e32 v196, v195, v196
	v_fmamk_f32 v123, v123, 0x3e38aa3b, v194
	v_fmamk_f32 v107, v107, 0x3e38aa3b, v194
	v_exp_f32_e32 v123, v123
	v_exp_f32_e32 v107, v107
	v_add_f32_e32 v195, v122, v106
	v_add_f32_e32 v196, v195, v196
	v_fmamk_f32 v124, v124, 0x3e38aa3b, v194
	v_fmamk_f32 v108, v108, 0x3e38aa3b, v194
	v_exp_f32_e32 v124, v124
	v_exp_f32_e32 v108, v108
	v_add_f32_e32 v195, v123, v107
	v_add_f32_e32 v196, v195, v196
	v_fmamk_f32 v125, v125, 0x3e38aa3b, v194
	v_fmamk_f32 v109, v109, 0x3e38aa3b, v194
	v_exp_f32_e32 v125, v125
	v_exp_f32_e32 v109, v109
	v_add_f32_e32 v195, v124, v108
	v_add_f32_e32 v196, v195, v196
	v_fmamk_f32 v126, v126, 0x3e38aa3b, v194
	v_fmamk_f32 v110, v110, 0x3e38aa3b, v194
	v_exp_f32_e32 v126, v126
	v_exp_f32_e32 v110, v110
	v_add_f32_e32 v195, v125, v109
	v_add_f32_e32 v196, v195, v196
	v_fmamk_f32 v127, v127, 0x3e38aa3b, v194
	v_fmamk_f32 v111, v111, 0x3e38aa3b, v194
	v_exp_f32_e32 v127, v127
	v_exp_f32_e32 v111, v111
	v_add_f32_e32 v195, v126, v110
	v_add_f32_e32 v196, v195, v196
	v_fmamk_f32 v128, v128, 0x3e38aa3b, v194
	v_fmamk_f32 v112, v112, 0x3e38aa3b, v194
	v_exp_f32_e32 v128, v128
	v_exp_f32_e32 v112, v112
	v_add_f32_e32 v195, v127, v111
	v_add_f32_e32 v196, v195, v196
	v_fmamk_f32 v129, v129, 0x3e38aa3b, v194
	v_fmamk_f32 v113, v113, 0x3e38aa3b, v194
	v_exp_f32_e32 v129, v129
	v_exp_f32_e32 v113, v113
	v_add_f32_e32 v195, v128, v112
	v_add_f32_e32 v196, v195, v196
	v_add_f32_e32 v195, v129, v113
	v_add_f32_e32 v196, v195, v196
	v_cmp_lt_f32_e32 vcc, 0x47800000, v196
	s_cbranch_vccnz .Lmy_rd_w
.Lmy_nrd_w:
	v_cvt_pk_bf16_f32 v208, v114, v115
	v_cvt_pk_bf16_f32 v209, v116, v117
	v_cvt_pk_bf16_f32 v210, v118, v119
	v_cvt_pk_bf16_f32 v211, v120, v121
	v_cvt_pk_bf16_f32 v105, v104, v105
	v_cvt_pk_bf16_f32 v104, v102, v103
	s_waitcnt lgkmcnt(0)
	v_mfma_f32_32x32x16_bf16 v[2:17], v[190:193], v[208:211], v[2:17]
	v_cvt_pk_bf16_f32 v103, v100, v101
	v_cvt_pk_bf16_f32 v102, v98, v99
	v_mfma_f32_32x32x16_bf16 v[18:33], v[174:177], v[208:211], v[18:33]
	v_cvt_pk_bf16_f32 v98, v106, v107
	v_cvt_pk_bf16_f32 v99, v108, v109
	v_cvt_pk_bf16_f32 v100, v110, v111
	v_cvt_pk_bf16_f32 v101, v112, v113
	v_cvt_pk_bf16_f32 v106, v122, v123
	v_cvt_pk_bf16_f32 v107, v124, v125
	v_cvt_pk_bf16_f32 v108, v126, v127
	v_cvt_pk_bf16_f32 v109, v128, v129
	v_add_f32_e32 v203, v196, v203
	s_nop 0
	v_mfma_f32_32x32x16_bf16 v[2:17], v[186:189], v[106:109], v[2:17]
	v_mfma_f32_32x32x16_bf16 v[18:33], v[170:173], v[106:109], v[18:33]
	v_mfma_f32_32x32x16_bf16 v[2:17], v[182:185], v[102:105], v[2:17]
	v_mfma_f32_32x32x16_bf16 v[18:33], v[166:169], v[102:105], v[18:33]
	v_mfma_f32_32x32x16_bf16 v[2:17], v[178:181], v[98:101], v[2:17]
	v_mfma_f32_32x32x16_bf16 v[18:33], v[162:165], v[98:101], v[18:33]
	s_mov_b32 s101, 0
	s_add_i32 s94, s94, 1
	s_xor_b32 s14, s14, 1
	s_add_i32 s13, s13, 64
	s_add_u32 s0, s0, 0x2000
	s_addc_u32 s1, s1, 0
	s_andn2_b64 vcc, exec, s[44:45]
	s_cbranch_vccz .LBB0_235
	v_mov_b32_e32 v242, v0
	s_branch .LBB0_412
.Lmy_rd_w:
	s_cmp_eq_u32 s101, 1
	s_cbranch_scc1 .Lmy_nrd_w
	s_mov_b32 s101, 1
	s_lshl_b32 s15, s14, 14
	s_branch .LBB0_414
